# bundle16 + last VGPR-address LDS-DMA in the P2 loop converted to SGPR-base form
# baseline (speedup 1.0000x reference)
.LBB0_379:
	ds_read_b128 v[130:133], v208
	ds_read_b128 v[134:137], v208 offset:1024
	ds_read_b128 v[138:141], v208 offset:2048
	ds_read_b128 v[142:145], v208 offset:3072
	ds_read_b128 v[146:149], v209
	ds_read_b128 v[150:153], v209 offset:1024
	ds_read_b128 v[154:157], v209 offset:2048
	ds_read_b128 v[158:161], v209 offset:3072
	s_add_u32 s56, s12, 0xffea0080
	s_addc_u32 s57, s13, -1
	s_cmpk_eq_i32 s83, 0x54
	s_cselect_b32 s59, s43, s57
	s_cselect_b32 s58, s42, s56
	s_cselect_b32 s57, s55, s82
	s_cselect_b32 s56, s54, s81
	s_add_i32 m0, s31, 0xc000
	ds_read_b128 v[162:165], v210
	ds_read_b128 v[166:169], v210 offset:1024
	ds_read_b128 v[170:173], v210 offset:2048
	ds_read_b128 v[174:177], v210 offset:3072
	ds_read_b128 v[196:199], v210 offset:4096
	ds_read_b128 v[200:203], v210 offset:5120
	ds_read_b128 v[212:215], v210 offset:6144
	ds_read_b128 v[216:219], v210 offset:7168
	global_load_lds_dwordx4 v188, s[12:13]
	s_add_i32 m0, s31, 0xe000
	s_nop 0
	global_load_lds_dwordx4 v190, s[12:13]
	s_waitcnt vmcnt(8)
	s_waitcnt lgkmcnt(0)
	s_setprio 1
	s_barrier
	v_mfma_f32_16x16x32_bf16 v[126:129], v[130:133], v[162:165], v[126:129]
	v_mfma_f32_16x16x32_bf16 v[122:125], v[138:141], v[162:165], v[122:125]
	v_mfma_f32_16x16x32_bf16 v[110:113], v[130:133], v[170:173], v[110:113]
	v_mfma_f32_16x16x32_bf16 v[106:109], v[138:141], v[170:173], v[106:109]
	v_mfma_f32_16x16x32_bf16 v[94:97], v[130:133], v[196:199], v[94:97]
	v_mfma_f32_16x16x32_bf16 v[90:93], v[138:141], v[196:199], v[90:93]
	v_mfma_f32_16x16x32_bf16 v[78:81], v[130:133], v[212:215], v[78:81]
	v_mfma_f32_16x16x32_bf16 v[74:77], v[138:141], v[212:215], v[74:77]
	v_mfma_f32_16x16x32_bf16 v[126:129], v[134:137], v[166:169], v[126:129]
	v_mfma_f32_16x16x32_bf16 v[122:125], v[142:145], v[166:169], v[122:125]
	v_mfma_f32_16x16x32_bf16 v[110:113], v[134:137], v[174:177], v[110:113]
	v_mfma_f32_16x16x32_bf16 v[106:109], v[142:145], v[174:177], v[106:109]
	v_mfma_f32_16x16x32_bf16 v[94:97], v[134:137], v[200:203], v[94:97]
	v_mfma_f32_16x16x32_bf16 v[90:93], v[142:145], v[200:203], v[90:93]
	v_mfma_f32_16x16x32_bf16 v[78:81], v[134:137], v[216:219], v[78:81]
	v_mfma_f32_16x16x32_bf16 v[74:77], v[142:145], v[216:219], v[74:77]
	s_setprio 0
	s_setprio 1
	v_mfma_f32_16x16x32_bf16 v[118:121], v[146:149], v[162:165], v[118:121]
	v_mfma_f32_16x16x32_bf16 v[114:117], v[154:157], v[162:165], v[114:117]
	v_mfma_f32_16x16x32_bf16 v[102:105], v[146:149], v[170:173], v[102:105]
	v_mfma_f32_16x16x32_bf16 v[98:101], v[154:157], v[170:173], v[98:101]
	v_mfma_f32_16x16x32_bf16 v[86:89], v[146:149], v[196:199], v[86:89]
	v_mfma_f32_16x16x32_bf16 v[82:85], v[154:157], v[196:199], v[82:85]
	v_mfma_f32_16x16x32_bf16 v[70:73], v[146:149], v[212:215], v[70:73]
	v_mfma_f32_16x16x32_bf16 v[66:69], v[154:157], v[212:215], v[66:69]
	v_mfma_f32_16x16x32_bf16 v[118:121], v[150:153], v[166:169], v[118:121]
	v_mfma_f32_16x16x32_bf16 v[114:117], v[158:161], v[166:169], v[114:117]
	v_mfma_f32_16x16x32_bf16 v[102:105], v[150:153], v[174:177], v[102:105]
	v_mfma_f32_16x16x32_bf16 v[98:101], v[158:161], v[174:177], v[98:101]
	v_mfma_f32_16x16x32_bf16 v[86:89], v[150:153], v[200:203], v[86:89]
	v_mfma_f32_16x16x32_bf16 v[82:85], v[158:161], v[200:203], v[82:85]
	v_mfma_f32_16x16x32_bf16 v[70:73], v[150:153], v[216:219], v[70:73]
	v_mfma_f32_16x16x32_bf16 v[66:69], v[158:161], v[216:219], v[66:69]
	s_barrier
	s_setprio 0
	s_add_i32 s85, s75, s29
	s_add_u32 s98, s56, 0x80
	s_addc_u32 s99, s57, 0
	s_mov_b32 m0, s85
	ds_read_b128 v[162:165], v210 offset:16384
	ds_read_b128 v[166:169], v210 offset:17408
	ds_read_b128 v[170:173], v210 offset:18432
	ds_read_b128 v[174:177], v210 offset:19456
	ds_read_b128 v[196:199], v210 offset:20480
	ds_read_b128 v[200:203], v210 offset:21504
	ds_read_b128 v[212:215], v210 offset:22528
	ds_read_b128 v[216:219], v210 offset:23552
	global_load_lds_dwordx4 v182, s[56:57]
	s_add_i32 m0, s85, 0x2000
	s_add_u32 s88, s56, 0x160000
	s_addc_u32 s89, s57, 0
	s_add_i32 s85, s76, s29
	global_load_lds_dwordx4 v186, s[56:57]
	s_mov_b32 m0, s85
	s_nop 0
	global_load_lds_dwordx4 v182, s[88:89]
	s_add_i32 m0, s85, 0x2000
	s_nop 0
	global_load_lds_dwordx4 v186, s[88:89]
	s_add_u32 s100, s58, 0x80
	s_addc_u32 s101, s59, 0
	s_mov_b32 m0, s31
	s_nop 0
	global_load_lds_dwordx4 v180, s[58:59]
	s_mov_b32 m0, s64
	s_nop 0
	global_load_lds_dwordx4 v184, s[58:59]
	s_waitcnt vmcnt(8)
	s_waitcnt lgkmcnt(0)
	s_setprio 1
	s_barrier
	v_mfma_f32_16x16x32_bf16 v[62:65], v[130:133], v[162:165], v[62:65]
	v_mfma_f32_16x16x32_bf16 v[58:61], v[138:141], v[162:165], v[58:61]
	v_mfma_f32_16x16x32_bf16 v[46:49], v[130:133], v[170:173], v[46:49]
	v_mfma_f32_16x16x32_bf16 v[42:45], v[138:141], v[170:173], v[42:45]
	v_mfma_f32_16x16x32_bf16 v[30:33], v[130:133], v[196:199], v[30:33]
	v_mfma_f32_16x16x32_bf16 v[26:29], v[138:141], v[196:199], v[26:29]
	v_mfma_f32_16x16x32_bf16 v[14:17], v[130:133], v[212:215], v[14:17]
	v_mfma_f32_16x16x32_bf16 v[10:13], v[138:141], v[212:215], v[10:13]
	v_mfma_f32_16x16x32_bf16 v[62:65], v[134:137], v[166:169], v[62:65]
	v_mfma_f32_16x16x32_bf16 v[58:61], v[142:145], v[166:169], v[58:61]
	v_mfma_f32_16x16x32_bf16 v[46:49], v[134:137], v[174:177], v[46:49]
	v_mfma_f32_16x16x32_bf16 v[42:45], v[142:145], v[174:177], v[42:45]
	v_mfma_f32_16x16x32_bf16 v[30:33], v[134:137], v[200:203], v[30:33]
	v_mfma_f32_16x16x32_bf16 v[26:29], v[142:145], v[200:203], v[26:29]
	v_mfma_f32_16x16x32_bf16 v[14:17], v[134:137], v[216:219], v[14:17]
	v_mfma_f32_16x16x32_bf16 v[10:13], v[142:145], v[216:219], v[10:13]
	s_setprio 0
	s_setprio 1
	v_mfma_f32_16x16x32_bf16 v[54:57], v[146:149], v[162:165], v[54:57]
	v_mfma_f32_16x16x32_bf16 v[50:53], v[154:157], v[162:165], v[50:53]
	v_mfma_f32_16x16x32_bf16 v[38:41], v[146:149], v[170:173], v[38:41]
	v_mfma_f32_16x16x32_bf16 v[34:37], v[154:157], v[170:173], v[34:37]
	v_mfma_f32_16x16x32_bf16 v[22:25], v[146:149], v[196:199], v[22:25]
	v_mfma_f32_16x16x32_bf16 v[18:21], v[154:157], v[196:199], v[18:21]
	v_mfma_f32_16x16x32_bf16 v[6:9], v[146:149], v[212:215], v[6:9]
	v_mfma_f32_16x16x32_bf16 v[2:5], v[154:157], v[212:215], v[2:5]
	v_mfma_f32_16x16x32_bf16 v[54:57], v[150:153], v[166:169], v[54:57]
	v_mfma_f32_16x16x32_bf16 v[50:53], v[158:161], v[166:169], v[50:53]
	v_mfma_f32_16x16x32_bf16 v[38:41], v[150:153], v[174:177], v[38:41]
	v_mfma_f32_16x16x32_bf16 v[34:37], v[158:161], v[174:177], v[34:37]
	v_mfma_f32_16x16x32_bf16 v[22:25], v[150:153], v[200:203], v[22:25]
	v_mfma_f32_16x16x32_bf16 v[18:21], v[158:161], v[200:203], v[18:21]
	v_mfma_f32_16x16x32_bf16 v[6:9], v[150:153], v[216:219], v[6:9]
	v_mfma_f32_16x16x32_bf16 v[2:5], v[158:161], v[216:219], v[2:5]
	s_barrier
	s_setprio 0
	s_add_i32 s85, 0, 0x18000
	s_add_i32 s87, 0, 0x1c000
	ds_read_b128 v[130:133], v208 offset:32768
	ds_read_b128 v[134:137], v208 offset:33792
	ds_read_b128 v[138:141], v208 offset:34816
	ds_read_b128 v[142:145], v208 offset:35840
	ds_read_b128 v[146:149], v209 offset:32768
	ds_read_b128 v[150:153], v209 offset:33792
	ds_read_b128 v[154:157], v209 offset:34816
	ds_read_b128 v[158:161], v209 offset:35840
	s_add_u32 s58, s58, 0x160000
	s_addc_u32 s59, s59, 0
	s_mov_b32 m0, s65
	ds_read_b128 v[162:165], v210 offset:32768
	ds_read_b128 v[166:169], v210 offset:33792
	ds_read_b128 v[170:173], v210 offset:34816
	ds_read_b128 v[174:177], v210 offset:35840
	ds_read_b128 v[196:199], v210 offset:36864
	ds_read_b128 v[200:203], v210 offset:37888
	ds_read_b128 v[212:215], v210 offset:38912
	ds_read_b128 v[216:219], v210 offset:39936
	global_load_lds_dwordx4 v180, s[58:59]
	s_mov_b32 m0, s66
	s_nop 0
	global_load_lds_dwordx4 v184, s[58:59]
	s_waitcnt vmcnt(8)
	s_waitcnt lgkmcnt(0)
	s_setprio 1
	s_barrier
	v_mfma_f32_16x16x32_bf16 v[126:129], v[130:133], v[162:165], v[126:129]
	v_mfma_f32_16x16x32_bf16 v[122:125], v[138:141], v[162:165], v[122:125]
	v_mfma_f32_16x16x32_bf16 v[110:113], v[130:133], v[170:173], v[110:113]
	v_mfma_f32_16x16x32_bf16 v[106:109], v[138:141], v[170:173], v[106:109]
	v_mfma_f32_16x16x32_bf16 v[94:97], v[130:133], v[196:199], v[94:97]
	v_mfma_f32_16x16x32_bf16 v[90:93], v[138:141], v[196:199], v[90:93]
	v_mfma_f32_16x16x32_bf16 v[78:81], v[130:133], v[212:215], v[78:81]
	v_mfma_f32_16x16x32_bf16 v[74:77], v[138:141], v[212:215], v[74:77]
	v_mfma_f32_16x16x32_bf16 v[126:129], v[134:137], v[166:169], v[126:129]
	v_mfma_f32_16x16x32_bf16 v[122:125], v[142:145], v[166:169], v[122:125]
	v_mfma_f32_16x16x32_bf16 v[110:113], v[134:137], v[174:177], v[110:113]
	v_mfma_f32_16x16x32_bf16 v[106:109], v[142:145], v[174:177], v[106:109]
	v_mfma_f32_16x16x32_bf16 v[94:97], v[134:137], v[200:203], v[94:97]
	v_mfma_f32_16x16x32_bf16 v[90:93], v[142:145], v[200:203], v[90:93]
	v_mfma_f32_16x16x32_bf16 v[78:81], v[134:137], v[216:219], v[78:81]
	v_mfma_f32_16x16x32_bf16 v[74:77], v[142:145], v[216:219], v[74:77]
	s_setprio 0
	s_setprio 1
	v_mfma_f32_16x16x32_bf16 v[118:121], v[146:149], v[162:165], v[118:121]
	v_mfma_f32_16x16x32_bf16 v[114:117], v[154:157], v[162:165], v[114:117]
	v_mfma_f32_16x16x32_bf16 v[102:105], v[146:149], v[170:173], v[102:105]
	v_mfma_f32_16x16x32_bf16 v[98:101], v[154:157], v[170:173], v[98:101]
	v_mfma_f32_16x16x32_bf16 v[86:89], v[146:149], v[196:199], v[86:89]
	v_mfma_f32_16x16x32_bf16 v[82:85], v[154:157], v[196:199], v[82:85]
	v_mfma_f32_16x16x32_bf16 v[70:73], v[146:149], v[212:215], v[70:73]
	v_mfma_f32_16x16x32_bf16 v[66:69], v[154:157], v[212:215], v[66:69]
	v_mfma_f32_16x16x32_bf16 v[118:121], v[150:153], v[166:169], v[118:121]
	v_mfma_f32_16x16x32_bf16 v[114:117], v[158:161], v[166:169], v[114:117]
	v_mfma_f32_16x16x32_bf16 v[102:105], v[150:153], v[174:177], v[102:105]
	v_mfma_f32_16x16x32_bf16 v[98:101], v[158:161], v[174:177], v[98:101]
	v_mfma_f32_16x16x32_bf16 v[86:89], v[150:153], v[200:203], v[86:89]
	v_mfma_f32_16x16x32_bf16 v[82:85], v[158:161], v[200:203], v[82:85]
	v_mfma_f32_16x16x32_bf16 v[70:73], v[150:153], v[216:219], v[70:73]
	v_mfma_f32_16x16x32_bf16 v[66:69], v[158:161], v[216:219], v[66:69]
	s_barrier
	s_setprio 0
	s_add_i32 s58, s85, s29
	s_mov_b32 m0, s58
	ds_read_b128 v[162:165], v210 offset:49152
	ds_read_b128 v[166:169], v210 offset:50176
	ds_read_b128 v[170:173], v210 offset:51200
	ds_read_b128 v[174:177], v210 offset:52224
	ds_read_b128 v[196:199], v210 offset:53248
	ds_read_b128 v[200:203], v210 offset:54272
	ds_read_b128 v[212:215], v210 offset:55296
	ds_read_b128 v[216:219], v210 offset:56320
	global_load_lds_dwordx4 v182, s[98:99]
	s_add_i32 m0, s58, 0x2000
	s_add_u32 s56, s56, 0x160080
	s_addc_u32 s57, s57, 0
	s_add_i32 s58, s87, s29
	global_load_lds_dwordx4 v186, s[98:99]
	s_mov_b32 m0, s58
	s_nop 0
	global_load_lds_dwordx4 v182, s[56:57]
	s_add_i32 m0, s58, 0x2000
	s_nop 0
	global_load_lds_dwordx4 v186, s[56:57]
	s_mov_b32 m0, s71
	s_nop 0
	global_load_lds_dwordx4 v180, s[100:101]
	s_mov_b32 m0, s72
	s_nop 0
	global_load_lds_dwordx4 v184, s[100:101]
	s_add_i32 s83, s83, 2
	s_add_u32 s12, s12, 0x100
	s_addc_u32 s13, s13, 0
	s_add_u32 s81, s81, 0x100
	s_addc_u32 s82, s82, 0
	s_cmpk_gt_u32 s83, 0x55
	s_waitcnt vmcnt(8)
	s_waitcnt lgkmcnt(0)
	s_setprio 1
	s_barrier
	v_mfma_f32_16x16x32_bf16 v[62:65], v[130:133], v[162:165], v[62:65]
	v_mfma_f32_16x16x32_bf16 v[58:61], v[138:141], v[162:165], v[58:61]
	v_mfma_f32_16x16x32_bf16 v[46:49], v[130:133], v[170:173], v[46:49]
	v_mfma_f32_16x16x32_bf16 v[42:45], v[138:141], v[170:173], v[42:45]
	v_mfma_f32_16x16x32_bf16 v[30:33], v[130:133], v[196:199], v[30:33]
	v_mfma_f32_16x16x32_bf16 v[26:29], v[138:141], v[196:199], v[26:29]
	v_mfma_f32_16x16x32_bf16 v[14:17], v[130:133], v[212:215], v[14:17]
	v_mfma_f32_16x16x32_bf16 v[10:13], v[138:141], v[212:215], v[10:13]
	v_mfma_f32_16x16x32_bf16 v[62:65], v[134:137], v[166:169], v[62:65]
	v_mfma_f32_16x16x32_bf16 v[58:61], v[142:145], v[166:169], v[58:61]
	v_mfma_f32_16x16x32_bf16 v[46:49], v[134:137], v[174:177], v[46:49]
	v_mfma_f32_16x16x32_bf16 v[42:45], v[142:145], v[174:177], v[42:45]
	v_mfma_f32_16x16x32_bf16 v[30:33], v[134:137], v[200:203], v[30:33]
	v_mfma_f32_16x16x32_bf16 v[26:29], v[142:145], v[200:203], v[26:29]
	v_mfma_f32_16x16x32_bf16 v[14:17], v[134:137], v[216:219], v[14:17]
	v_mfma_f32_16x16x32_bf16 v[10:13], v[142:145], v[216:219], v[10:13]
	s_setprio 0
	s_setprio 1
	v_mfma_f32_16x16x32_bf16 v[54:57], v[146:149], v[162:165], v[54:57]
	v_mfma_f32_16x16x32_bf16 v[50:53], v[154:157], v[162:165], v[50:53]
	v_mfma_f32_16x16x32_bf16 v[38:41], v[146:149], v[170:173], v[38:41]
	v_mfma_f32_16x16x32_bf16 v[34:37], v[154:157], v[170:173], v[34:37]
	v_mfma_f32_16x16x32_bf16 v[22:25], v[146:149], v[196:199], v[22:25]
	v_mfma_f32_16x16x32_bf16 v[18:21], v[154:157], v[196:199], v[18:21]
	v_mfma_f32_16x16x32_bf16 v[6:9], v[146:149], v[212:215], v[6:9]
	v_mfma_f32_16x16x32_bf16 v[2:5], v[154:157], v[212:215], v[2:5]
	v_mfma_f32_16x16x32_bf16 v[54:57], v[150:153], v[166:169], v[54:57]
	v_mfma_f32_16x16x32_bf16 v[50:53], v[158:161], v[166:169], v[50:53]
	v_mfma_f32_16x16x32_bf16 v[38:41], v[150:153], v[174:177], v[38:41]
	v_mfma_f32_16x16x32_bf16 v[34:37], v[158:161], v[174:177], v[34:37]
	v_mfma_f32_16x16x32_bf16 v[22:25], v[150:153], v[200:203], v[22:25]
	v_mfma_f32_16x16x32_bf16 v[18:21], v[158:161], v[200:203], v[18:21]
	v_mfma_f32_16x16x32_bf16 v[6:9], v[150:153], v[216:219], v[6:9]
	v_mfma_f32_16x16x32_bf16 v[2:5], v[158:161], v[216:219], v[2:5]
	s_barrier
	s_setprio 0
	s_cbranch_scc0 .LBB0_379
	s_and_b64 vcc, exec, s[34:35]
	s_cbranch_vccz .LBB0_382
	s_barrier
